# SwiGLU epilogue: packed multiply by -log2e (constant pair in VGPRs)
# baseline (speedup 1.0000x reference)
.Lpost_555:
	v_lshl_or_b32 v136, s46, 7, v140
	v_lshl_add_u32 v142, s48, 8, v138
	v_ashrrev_i32_e32 v137, 31, v136
	v_mov_b64_e32 v[134:135], s[30:31]
	v_lshlrev_b64 v[136:137], 1, v[136:137]
	s_and_b64 vcc, exec, s[38:39]
	s_mov_b32 s48, s42
	s_mov_b32 s46, s40
	v_mov_b32_e32 v188, 0xbfb8aa3b
	v_mov_b32_e32 v189, 0xbfb8aa3b
	v_mad_i64_i32 v[144:145], s[2:3], v142, s33, v[134:135]
	v_or_b32_e32 v186, 16, v142
	v_pk_mul_f32 v[162:163], v[124:125], v[188:189]
	v_mad_i64_i32 v[186:187], s[2:3], v186, s33, v[134:135]
	v_pk_mul_f32 v[164:165], v[126:127], v[188:189]
	v_pk_mul_f32 v[170:171], v[108:109], v[188:189]
	v_pk_mul_f32 v[166:167], v[116:117], v[188:189]
	v_pk_mul_f32 v[172:173], v[110:111], v[188:189]
	v_pk_mul_f32 v[168:169], v[118:119], v[188:189]
	v_pk_mul_f32 v[174:175], v[100:101], v[188:189]
	v_lshl_add_u64 v[144:145], v[144:145], 0, v[136:137]
	v_pk_mul_f32 v[176:177], v[102:103], v[188:189]
	v_exp_f32_e32 v162, v162
	v_lshl_add_u64 v[186:187], v[186:187], 0, v[136:137]
	v_exp_f32_e32 v163, v163
	v_exp_f32_e32 v170, v170
	v_exp_f32_e32 v164, v164
	v_exp_f32_e32 v171, v171
	v_exp_f32_e32 v165, v165
	v_exp_f32_e32 v172, v172
	v_exp_f32_e32 v166, v166
	v_exp_f32_e32 v173, v173
	v_exp_f32_e32 v167, v167
	v_exp_f32_e32 v174, v174
	v_exp_f32_e32 v168, v168
	v_exp_f32_e32 v175, v175
	v_exp_f32_e32 v169, v169
	v_exp_f32_e32 v176, v176
	v_pk_add_f32 v[162:163], v[162:163], 1.0 op_sel_hi:[1,0]
	v_exp_f32_e32 v177, v177
	v_pk_add_f32 v[164:165], v[164:165], 1.0 op_sel_hi:[1,0]
	v_pk_add_f32 v[170:171], v[170:171], 1.0 op_sel_hi:[1,0]
	v_pk_add_f32 v[166:167], v[166:167], 1.0 op_sel_hi:[1,0]
	v_pk_add_f32 v[172:173], v[172:173], 1.0 op_sel_hi:[1,0]
	v_pk_add_f32 v[168:169], v[168:169], 1.0 op_sel_hi:[1,0]
	v_pk_add_f32 v[174:175], v[174:175], 1.0 op_sel_hi:[1,0]
	v_rcp_f32_e32 v162, v162
	v_pk_add_f32 v[176:177], v[176:177], 1.0 op_sel_hi:[1,0]
	v_rcp_f32_e32 v163, v163
	v_rcp_f32_e32 v170, v170
	v_rcp_f32_e32 v164, v164
	v_rcp_f32_e32 v171, v171
	v_rcp_f32_e32 v165, v165
	v_rcp_f32_e32 v172, v172
	v_rcp_f32_e32 v166, v166
	v_rcp_f32_e32 v173, v173
	v_rcp_f32_e32 v167, v167
	v_rcp_f32_e32 v174, v174
	v_rcp_f32_e32 v168, v168
	v_rcp_f32_e32 v175, v175
	v_rcp_f32_e32 v169, v169
	v_rcp_f32_e32 v176, v176
	v_pk_mul_f32 v[162:163], v[124:125], v[162:163]
	v_rcp_f32_e32 v177, v177
	v_pk_mul_f32 v[164:165], v[126:127], v[164:165]
	v_pk_mul_f32 v[170:171], v[108:109], v[170:171]
	v_pk_mul_f32 v[166:167], v[116:117], v[166:167]
	v_pk_mul_f32 v[172:173], v[110:111], v[172:173]
	v_pk_mul_f32 v[168:169], v[118:119], v[168:169]
	v_pk_mul_f32 v[174:175], v[100:101], v[174:175]
	v_pk_mul_f32 v[162:163], v[162:163], v[120:121]
	v_pk_mul_f32 v[176:177], v[102:103], v[176:177]
	v_pk_mul_f32 v[164:165], v[164:165], v[122:123]
	v_pk_mul_f32 v[170:171], v[170:171], v[104:105]
	v_pk_mul_f32 v[166:167], v[166:167], v[112:113]
	v_pk_mul_f32 v[172:173], v[172:173], v[106:107]
	v_pk_mul_f32 v[168:169], v[168:169], v[114:115]
	v_pk_mul_f32 v[174:175], v[174:175], v[96:97]
	v_cvt_pk_bf16_f32 v178, v162, v163
	v_pk_mul_f32 v[176:177], v[176:177], v[98:99]
	v_cvt_pk_bf16_f32 v179, v164, v165
	v_cvt_pk_bf16_f32 v182, v170, v171
	v_cvt_pk_bf16_f32 v180, v166, v167
	v_cvt_pk_bf16_f32 v183, v172, v173
	v_cvt_pk_bf16_f32 v181, v168, v169
	v_cvt_pk_bf16_f32 v184, v174, v175
	global_store_dwordx4 v[144:145], v[178:181], off
	v_cvt_pk_bf16_f32 v185, v176, v177
	global_store_dwordx4 v[186:187], v[182:185], off
	v_or_b32_e32 v144, 32, v142
	v_or_b32_e32 v186, 48, v142
	v_mad_i64_i32 v[144:145], s[2:3], v144, s33, v[134:135]
	v_mad_i64_i32 v[186:187], s[2:3], v186, s33, v[134:135]
	v_pk_mul_f32 v[162:163], v[92:93], v[188:189]
	v_pk_mul_f32 v[170:171], v[76:77], v[188:189]
	v_pk_mul_f32 v[164:165], v[94:95], v[188:189]
	v_pk_mul_f32 v[172:173], v[78:79], v[188:189]
	v_pk_mul_f32 v[166:167], v[84:85], v[188:189]
	v_pk_mul_f32 v[174:175], v[68:69], v[188:189]
	v_pk_mul_f32 v[168:169], v[86:87], v[188:189]
	v_pk_mul_f32 v[176:177], v[70:71], v[188:189]
	v_lshl_add_u64 v[144:145], v[144:145], 0, v[136:137]
	v_lshl_add_u64 v[186:187], v[186:187], 0, v[136:137]
	v_exp_f32_e32 v162, v162
	v_exp_f32_e32 v170, v170
	v_exp_f32_e32 v163, v163
	v_exp_f32_e32 v171, v171
	v_exp_f32_e32 v164, v164
	v_exp_f32_e32 v172, v172
	v_exp_f32_e32 v165, v165
	v_exp_f32_e32 v173, v173
	v_exp_f32_e32 v166, v166
	v_exp_f32_e32 v174, v174
	v_exp_f32_e32 v167, v167
	v_exp_f32_e32 v175, v175
	v_exp_f32_e32 v168, v168
	v_exp_f32_e32 v176, v176
	v_exp_f32_e32 v169, v169
	v_exp_f32_e32 v177, v177
	v_pk_add_f32 v[162:163], v[162:163], 1.0 op_sel_hi:[1,0]
	v_pk_add_f32 v[170:171], v[170:171], 1.0 op_sel_hi:[1,0]
	v_pk_add_f32 v[164:165], v[164:165], 1.0 op_sel_hi:[1,0]
	v_pk_add_f32 v[172:173], v[172:173], 1.0 op_sel_hi:[1,0]
	v_pk_add_f32 v[166:167], v[166:167], 1.0 op_sel_hi:[1,0]
	v_pk_add_f32 v[174:175], v[174:175], 1.0 op_sel_hi:[1,0]
	v_pk_add_f32 v[168:169], v[168:169], 1.0 op_sel_hi:[1,0]
	v_pk_add_f32 v[176:177], v[176:177], 1.0 op_sel_hi:[1,0]
	v_rcp_f32_e32 v162, v162
	v_rcp_f32_e32 v170, v170
	v_rcp_f32_e32 v163, v163
	v_rcp_f32_e32 v171, v171
	v_rcp_f32_e32 v164, v164
	v_rcp_f32_e32 v172, v172
	v_rcp_f32_e32 v165, v165
	v_rcp_f32_e32 v173, v173
	v_rcp_f32_e32 v166, v166
	v_rcp_f32_e32 v174, v174
	v_rcp_f32_e32 v167, v167
	v_rcp_f32_e32 v175, v175
	v_rcp_f32_e32 v168, v168
	v_rcp_f32_e32 v176, v176
	v_rcp_f32_e32 v169, v169
	v_rcp_f32_e32 v177, v177
	v_pk_mul_f32 v[162:163], v[92:93], v[162:163]
	v_pk_mul_f32 v[170:171], v[76:77], v[170:171]
	v_pk_mul_f32 v[164:165], v[94:95], v[164:165]
	v_pk_mul_f32 v[172:173], v[78:79], v[172:173]
	v_pk_mul_f32 v[166:167], v[84:85], v[166:167]
	v_pk_mul_f32 v[174:175], v[68:69], v[174:175]
	v_pk_mul_f32 v[168:169], v[86:87], v[168:169]
	v_pk_mul_f32 v[176:177], v[70:71], v[176:177]
	v_pk_mul_f32 v[162:163], v[162:163], v[88:89]
	v_pk_mul_f32 v[170:171], v[170:171], v[72:73]
	v_pk_mul_f32 v[164:165], v[164:165], v[90:91]
	v_pk_mul_f32 v[172:173], v[172:173], v[74:75]
	v_pk_mul_f32 v[166:167], v[166:167], v[80:81]
	v_pk_mul_f32 v[174:175], v[174:175], v[64:65]
	v_pk_mul_f32 v[168:169], v[168:169], v[82:83]
	v_pk_mul_f32 v[176:177], v[176:177], v[66:67]
	v_cvt_pk_bf16_f32 v178, v162, v163
	v_cvt_pk_bf16_f32 v182, v170, v171
	v_cvt_pk_bf16_f32 v179, v164, v165
	v_cvt_pk_bf16_f32 v183, v172, v173
	v_cvt_pk_bf16_f32 v180, v166, v167
	v_cvt_pk_bf16_f32 v184, v174, v175
	v_cvt_pk_bf16_f32 v181, v168, v169
	v_cvt_pk_bf16_f32 v185, v176, v177
	global_store_dwordx4 v[144:145], v[178:181], off
	global_store_dwordx4 v[186:187], v[182:185], off
	v_add_u32_e32 v144, 0x80, v142
	v_add_u32_e32 v186, 0x90, v142
	v_mad_i64_i32 v[144:145], s[2:3], v144, s33, v[134:135]
	v_mad_i64_i32 v[186:187], s[2:3], v186, s33, v[134:135]
	v_pk_mul_f32 v[162:163], v[60:61], v[188:189]
	v_pk_mul_f32 v[170:171], v[44:45], v[188:189]
	v_pk_mul_f32 v[164:165], v[62:63], v[188:189]
	v_pk_mul_f32 v[172:173], v[46:47], v[188:189]
	v_pk_mul_f32 v[166:167], v[52:53], v[188:189]
	v_pk_mul_f32 v[174:175], v[36:37], v[188:189]
	v_pk_mul_f32 v[168:169], v[54:55], v[188:189]
	v_pk_mul_f32 v[176:177], v[38:39], v[188:189]
	v_lshl_add_u64 v[144:145], v[144:145], 0, v[136:137]
	v_lshl_add_u64 v[186:187], v[186:187], 0, v[136:137]
	v_exp_f32_e32 v162, v162
	v_exp_f32_e32 v170, v170
	v_exp_f32_e32 v163, v163
	v_exp_f32_e32 v171, v171
	v_exp_f32_e32 v164, v164
	v_exp_f32_e32 v172, v172
	v_exp_f32_e32 v165, v165
	v_exp_f32_e32 v173, v173
	v_exp_f32_e32 v166, v166
	v_exp_f32_e32 v174, v174
	v_exp_f32_e32 v167, v167
	v_exp_f32_e32 v175, v175
	v_exp_f32_e32 v168, v168
	v_exp_f32_e32 v176, v176
	v_exp_f32_e32 v169, v169
	v_exp_f32_e32 v177, v177
	v_pk_add_f32 v[162:163], v[162:163], 1.0 op_sel_hi:[1,0]
	v_pk_add_f32 v[170:171], v[170:171], 1.0 op_sel_hi:[1,0]
	v_pk_add_f32 v[164:165], v[164:165], 1.0 op_sel_hi:[1,0]
	v_pk_add_f32 v[172:173], v[172:173], 1.0 op_sel_hi:[1,0]
	v_pk_add_f32 v[166:167], v[166:167], 1.0 op_sel_hi:[1,0]
	v_pk_add_f32 v[174:175], v[174:175], 1.0 op_sel_hi:[1,0]
	v_pk_add_f32 v[168:169], v[168:169], 1.0 op_sel_hi:[1,0]
	v_pk_add_f32 v[176:177], v[176:177], 1.0 op_sel_hi:[1,0]
	v_rcp_f32_e32 v162, v162
	v_rcp_f32_e32 v170, v170
	v_rcp_f32_e32 v163, v163
	v_rcp_f32_e32 v171, v171
	v_rcp_f32_e32 v164, v164
	v_rcp_f32_e32 v172, v172
	v_rcp_f32_e32 v165, v165
	v_rcp_f32_e32 v173, v173
	v_rcp_f32_e32 v166, v166
	v_rcp_f32_e32 v174, v174
	v_rcp_f32_e32 v167, v167
	v_rcp_f32_e32 v175, v175
	v_rcp_f32_e32 v168, v168
	v_rcp_f32_e32 v176, v176
	v_rcp_f32_e32 v169, v169
	v_rcp_f32_e32 v177, v177
	v_pk_mul_f32 v[162:163], v[60:61], v[162:163]
	v_pk_mul_f32 v[170:171], v[44:45], v[170:171]
	v_pk_mul_f32 v[164:165], v[62:63], v[164:165]
	v_pk_mul_f32 v[172:173], v[46:47], v[172:173]
	v_pk_mul_f32 v[166:167], v[52:53], v[166:167]
	v_pk_mul_f32 v[174:175], v[36:37], v[174:175]
	v_pk_mul_f32 v[168:169], v[54:55], v[168:169]
	v_pk_mul_f32 v[176:177], v[38:39], v[176:177]
	v_pk_mul_f32 v[162:163], v[162:163], v[56:57]
	v_pk_mul_f32 v[170:171], v[170:171], v[40:41]
	v_pk_mul_f32 v[164:165], v[164:165], v[58:59]
	v_pk_mul_f32 v[172:173], v[172:173], v[42:43]
	v_pk_mul_f32 v[166:167], v[166:167], v[48:49]
	v_pk_mul_f32 v[174:175], v[174:175], v[32:33]
	v_pk_mul_f32 v[168:169], v[168:169], v[50:51]
	v_pk_mul_f32 v[176:177], v[176:177], v[34:35]
	v_cvt_pk_bf16_f32 v178, v162, v163
	v_cvt_pk_bf16_f32 v182, v170, v171
	v_cvt_pk_bf16_f32 v179, v164, v165
	v_cvt_pk_bf16_f32 v183, v172, v173
	v_cvt_pk_bf16_f32 v180, v166, v167
	v_cvt_pk_bf16_f32 v184, v174, v175
	v_cvt_pk_bf16_f32 v181, v168, v169
	v_cvt_pk_bf16_f32 v185, v176, v177
	global_store_dwordx4 v[144:145], v[178:181], off
	global_store_dwordx4 v[186:187], v[182:185], off
	v_add_u32_e32 v144, 0xa0, v142
	v_add_u32_e32 v186, 0xb0, v142
	v_mad_i64_i32 v[144:145], s[2:3], v144, s33, v[134:135]
	v_mad_i64_i32 v[186:187], s[2:3], v186, s33, v[134:135]
	v_pk_mul_f32 v[162:163], v[28:29], v[188:189]
	v_pk_mul_f32 v[170:171], v[12:13], v[188:189]
	v_pk_mul_f32 v[164:165], v[30:31], v[188:189]
	v_pk_mul_f32 v[172:173], v[14:15], v[188:189]
	v_pk_mul_f32 v[166:167], v[20:21], v[188:189]
	v_pk_mul_f32 v[174:175], v[4:5], v[188:189]
	v_pk_mul_f32 v[168:169], v[22:23], v[188:189]
	v_pk_mul_f32 v[176:177], v[6:7], v[188:189]
	v_lshl_add_u64 v[144:145], v[144:145], 0, v[136:137]
	v_lshl_add_u64 v[186:187], v[186:187], 0, v[136:137]
	v_exp_f32_e32 v162, v162
	v_exp_f32_e32 v170, v170
	v_exp_f32_e32 v163, v163
	v_exp_f32_e32 v171, v171
	v_exp_f32_e32 v164, v164
	v_exp_f32_e32 v172, v172
	v_exp_f32_e32 v165, v165
	v_exp_f32_e32 v173, v173
	v_exp_f32_e32 v166, v166
	v_exp_f32_e32 v174, v174
	v_exp_f32_e32 v167, v167
	v_exp_f32_e32 v175, v175
	v_exp_f32_e32 v168, v168
	v_exp_f32_e32 v176, v176
	v_exp_f32_e32 v169, v169
	v_exp_f32_e32 v177, v177
	v_pk_add_f32 v[162:163], v[162:163], 1.0 op_sel_hi:[1,0]
	v_pk_add_f32 v[170:171], v[170:171], 1.0 op_sel_hi:[1,0]
	v_pk_add_f32 v[164:165], v[164:165], 1.0 op_sel_hi:[1,0]
	v_pk_add_f32 v[172:173], v[172:173], 1.0 op_sel_hi:[1,0]
	v_pk_add_f32 v[166:167], v[166:167], 1.0 op_sel_hi:[1,0]
	v_pk_add_f32 v[174:175], v[174:175], 1.0 op_sel_hi:[1,0]
	v_pk_add_f32 v[168:169], v[168:169], 1.0 op_sel_hi:[1,0]
	v_pk_add_f32 v[176:177], v[176:177], 1.0 op_sel_hi:[1,0]
	v_rcp_f32_e32 v162, v162
	v_rcp_f32_e32 v170, v170
	v_rcp_f32_e32 v163, v163
	v_rcp_f32_e32 v171, v171
	v_rcp_f32_e32 v164, v164
	v_rcp_f32_e32 v172, v172
	v_rcp_f32_e32 v165, v165
	v_rcp_f32_e32 v173, v173
	v_rcp_f32_e32 v166, v166
	v_rcp_f32_e32 v174, v174
	v_rcp_f32_e32 v167, v167
	v_rcp_f32_e32 v175, v175
	v_rcp_f32_e32 v168, v168
	v_rcp_f32_e32 v176, v176
	v_rcp_f32_e32 v169, v169
	v_rcp_f32_e32 v177, v177
	v_pk_mul_f32 v[162:163], v[28:29], v[162:163]
	v_pk_mul_f32 v[170:171], v[12:13], v[170:171]
	v_pk_mul_f32 v[164:165], v[30:31], v[164:165]
	v_pk_mul_f32 v[172:173], v[14:15], v[172:173]
	v_pk_mul_f32 v[166:167], v[20:21], v[166:167]
	v_pk_mul_f32 v[174:175], v[4:5], v[174:175]
	v_pk_mul_f32 v[168:169], v[22:23], v[168:169]
	v_pk_mul_f32 v[176:177], v[6:7], v[176:177]
	v_pk_mul_f32 v[162:163], v[162:163], v[24:25]
	v_pk_mul_f32 v[170:171], v[170:171], v[8:9]
	v_pk_mul_f32 v[164:165], v[164:165], v[26:27]
	v_pk_mul_f32 v[172:173], v[172:173], v[10:11]
	v_pk_mul_f32 v[166:167], v[166:167], v[16:17]
	v_pk_mul_f32 v[174:175], v[174:175], v[0:1]
	v_pk_mul_f32 v[168:169], v[168:169], v[18:19]
	v_pk_mul_f32 v[176:177], v[176:177], v[2:3]
	v_cvt_pk_bf16_f32 v178, v162, v163
	v_cvt_pk_bf16_f32 v182, v170, v171
	v_cvt_pk_bf16_f32 v179, v164, v165
	v_cvt_pk_bf16_f32 v183, v172, v173
	v_cvt_pk_bf16_f32 v180, v166, v167
	v_cvt_pk_bf16_f32 v184, v174, v175
	v_cvt_pk_bf16_f32 v181, v168, v169
	v_cvt_pk_bf16_f32 v185, v176, v177
	global_store_dwordx4 v[144:145], v[178:181], off
	global_store_dwordx4 v[186:187], v[182:185], off
	s_cbranch_vccz .LBB0_554
	s_waitcnt vmcnt(0)
	s_cmpk_gt_u32 s21, 0xff
	s_cbranch_scc1 .LBB0_559
	s_barrier
